# v027_eloop
# speedup vs baseline: 1.0078x; 1.0066x over previous
; __device__ __forceinline__ void ssm_prep_item(const Params& p, int lg) {
;     ...
;   for (int it = tid; it < 128 * 64; it += NTHR) {
;     int r = it >> 6, s = it & 63, pp = r & 63;
;     float pr = powre[pp * 68 + 63 - s], pi = powim[pp * 68 + 63 - s];
;     unsigned o[8];
; #pragma unroll
;     for (int c2 = 0; c2 < 8; ++c2) {
;       float v0, v1;
;       float b0r = bbre[pp * 16 + 2 * c2], b0i = bbim[pp * 16 + 2 * c2];
;       float b1r = bbre[pp * 16 + 2 * c2 + 1], b1i = bbim[pp * 16 + 2 * c2 + 1];
;       if (r < 64) { v0 = pr * b0r - pi * b0i; v1 = pr * b1r - pi * b1i; }
;       else { v0 = pr * b0i + pi * b0r; v1 = pr * b1i + pi * b1r; }
;       o[c2] = pack2(v0, v1);
;     }
;     u16* d = E + ((size_t)((r >> 5) * 64 + s) * 64 + (r & 31)) * 8;
;     *reinterpret_cast<u32x4*>(d) = u32x4{o[0], o[1], o[2], o[3]};
;     *reinterpret_cast<u32x4*>(d + 32 * 8) = u32x4{o[4], o[5], o[6], o[7]};
;   }
.LBB0_292:
	v_and_b32_e32 v83, 0x1e00, v61
	v_and_b32_e32 v84, 7, v61
	v_lshl_or_b32 v83, v84, 6, v83
	v_bfe_u32 v84, v61, 6, 3
	v_lshl_or_b32 v83, v84, 3, v83
	v_bfe_u32 v84, v61, 3, 3
	v_or_b32_e32 v83, v83, v84
	v_and_b32_e32 v84, 63, v83
	v_sub_u32_e32 v85, 63, v84
	v_ashrrev_i32_e32 v65, 6, v83
	v_and_b32_e32 v0, 63, v65
	v_mad_u32_u24 v1, v0, s33, v85
	v_lshl_add_u32 v0, v0, 6, 32
	v_lshl_add_u32 v1, v1, 2, 32
	v_add_u32_e32 v14, 0x8800, v0
	v_add_u32_e32 v18, 0x9800, v0
	ds_read2st64_b32 v[62:63], v1 offset1:68
	ds_read2_b64 v[0:3], v14 offset1:1
	ds_read2_b64 v[6:9], v14 offset0:2 offset1:3
	ds_read2_b64 v[10:13], v14 offset0:4 offset1:5
	ds_read2_b64 v[14:17], v14 offset0:6 offset1:7
	ds_read2_b64 v[22:25], v18 offset1:1
	ds_read2_b64 v[38:41], v18 offset0:2 offset1:3
	ds_read2_b64 v[42:45], v18 offset0:4 offset1:5
	ds_read2_b64 v[46:49], v18 offset0:6 offset1:7
	s_waitcnt lgkmcnt(7)
	v_mov_b32_e32 v18, v0
	s_waitcnt lgkmcnt(3)
	v_mov_b32_e32 v19, v22
	v_mov_b32_e32 v22, v1
	v_mov_b32_e32 v66, v63
	v_mov_b32_e32 v67, v62
	v_mov_b32_e32 v0, v2
	v_mov_b32_e32 v1, v24
	v_mov_b32_e32 v24, v3
	v_mov_b32_e32 v2, v6
	s_waitcnt lgkmcnt(2)
	v_mov_b32_e32 v3, v38
	v_mov_b32_e32 v38, v7
	v_mov_b32_e32 v6, v8
	v_mov_b32_e32 v7, v40
	v_mov_b32_e32 v40, v9
	v_mov_b32_e32 v50, v10
	s_waitcnt lgkmcnt(1)
	v_mov_b32_e32 v51, v42
	v_mov_b32_e32 v42, v11
	v_mov_b32_e32 v68, v12
	v_mov_b32_e32 v69, v44
	v_mov_b32_e32 v44, v13
	v_mov_b32_e32 v70, v14
	s_waitcnt lgkmcnt(0)
	v_mov_b32_e32 v71, v46
	v_mov_b32_e32 v46, v15
	v_mov_b32_e32 v72, v16
	v_mov_b32_e32 v73, v48
	v_mov_b32_e32 v48, v17
	s_movk_i32 s20, 0x1dff
	v_pk_mul_f32 v[74:75], v[62:63], v[18:19]
	v_pk_mul_f32 v[76:77], v[62:63], v[22:23]
	v_pk_mul_f32 v[78:79], v[66:67], v[18:19]
	v_pk_mul_f32 v[58:59], v[66:67], v[22:23]
	v_pk_mul_f32 v[18:19], v[62:63], v[0:1]
	v_pk_mul_f32 v[20:21], v[62:63], v[24:25]
	v_pk_mul_f32 v[22:23], v[66:67], v[0:1]
	v_pk_mul_f32 v[24:25], v[66:67], v[24:25]
	v_pk_mul_f32 v[28:29], v[62:63], v[38:39]
	v_pk_mul_f32 v[30:31], v[66:67], v[2:3]
	v_pk_mul_f32 v[32:33], v[66:67], v[38:39]
	v_pk_mul_f32 v[34:35], v[62:63], v[6:7]
	v_pk_mul_f32 v[36:37], v[62:63], v[40:41]
	v_pk_mul_f32 v[38:39], v[66:67], v[6:7]
	v_pk_mul_f32 v[40:41], v[66:67], v[40:41]
	v_pk_mul_f32 v[16:17], v[62:63], v[42:43]
	v_pk_mul_f32 v[14:15], v[66:67], v[42:43]
	v_pk_mul_f32 v[10:11], v[66:67], v[44:45]
	v_pk_mul_f32 v[8:9], v[62:63], v[46:47]
	v_pk_mul_f32 v[6:7], v[66:67], v[46:47]
	v_pk_mul_f32 v[0:1], v[66:67], v[48:49]
	v_pk_mul_f32 v[56:57], v[62:63], v[50:51]
	v_pk_mul_f32 v[54:55], v[66:67], v[50:51]
	v_pk_mul_f32 v[50:51], v[66:67], v[68:69]
	v_pk_mul_f32 v[46:47], v[66:67], v[70:71]
	v_pk_mul_f32 v[42:43], v[66:67], v[72:73]
	v_ashrrev_i32_e32 v66, 5, v83
	v_cmp_lt_i32_e32 vcc, s20, v61
	s_movk_i32 s20, 0xffc0
	v_add_f32_e32 v67, v58, v59
	v_and_or_b32 v58, v66, s20, v84
	v_ashrrev_i32_e32 v59, 31, v58
	v_pk_mul_f32 v[26:27], v[62:63], v[2:3]
	v_pk_mul_f32 v[12:13], v[62:63], v[44:45]
	v_pk_mul_f32 v[2:3], v[62:63], v[48:49]
	v_pk_mul_f32 v[52:53], v[62:63], v[68:69]
	v_pk_mul_f32 v[48:49], v[62:63], v[70:71]
	v_pk_mul_f32 v[44:45], v[62:63], v[72:73]
	v_lshlrev_b32_e32 v62, 4, v65
	v_sub_f32_e32 v63, v76, v77
	s_or_b64 s[18:19], vcc, s[18:19]
	v_lshlrev_b64 v[58:59], 10, v[58:59]
	v_cmp_gt_i32_e32 vcc, 64, v65
	v_and_b32_e32 v162, 0x1f0, v62
	v_sub_f32_e32 v62, v74, v75
	v_add_f32_e32 v64, v78, v79
	v_lshl_add_u64 v[58:59], s[10:11], 0, v[58:59]
	v_sub_f32_e32 v18, v18, v19
	v_sub_f32_e32 v19, v20, v21
	v_add_f32_e32 v20, v22, v23
	v_add_f32_e32 v21, v24, v25
	v_sub_f32_e32 v22, v26, v27
	v_sub_f32_e32 v23, v28, v29
	v_add_f32_e32 v24, v30, v31
	v_add_f32_e32 v25, v32, v33
	v_sub_f32_e32 v26, v34, v35
	v_sub_f32_e32 v27, v36, v37
	v_add_f32_e32 v28, v38, v39
	v_add_f32_e32 v29, v40, v41
	v_add_f32_e32 v14, v14, v15
	v_sub_f32_e32 v15, v52, v53
	v_sub_f32_e32 v12, v12, v13
	v_add_f32_e32 v13, v50, v51
	v_add_f32_e32 v10, v10, v11
	v_sub_f32_e32 v11, v48, v49
	v_sub_f32_e32 v8, v8, v9
	v_add_f32_e32 v9, v46, v47
	v_add_f32_e32 v6, v6, v7
	v_sub_f32_e32 v7, v44, v45
	v_sub_f32_e32 v2, v2, v3
	v_add_f32_e32 v3, v42, v43
	v_add_f32_e32 v0, v0, v1
	v_cndmask_b32_e32 v1, v67, v63, vcc
	v_add_u32_e32 v61, 0x200, v61
	v_lshl_add_u64 v[58:59], v[58:59], 0, v[162:163]
	v_sub_f32_e32 v30, v56, v57
	v_sub_f32_e32 v16, v16, v17
	v_add_f32_e32 v17, v54, v55
	v_cndmask_b32_e32 v31, v64, v62, vcc
	v_cndmask_b32_e32 v19, v21, v19, vcc
	v_cndmask_b32_e32 v18, v20, v18, vcc
	v_cndmask_b32_e32 v20, v25, v23, vcc
	v_cndmask_b32_e32 v21, v24, v22, vcc
	v_cndmask_b32_e32 v22, v29, v27, vcc
	v_cndmask_b32_e32 v23, v28, v26, vcc
	v_cndmask_b32_e32 v10, v10, v12, vcc
	v_cndmask_b32_e32 v12, v13, v15, vcc
	v_cndmask_b32_e32 v8, v6, v8, vcc
	v_cndmask_b32_e32 v9, v9, v11, vcc
	v_cndmask_b32_e32 v11, v0, v2, vcc
	v_cndmask_b32_e32 v13, v3, v7, vcc
	v_cvt_pk_bf16_f32 v0, v31, v1
	v_cvt_pk_bf16_f32 v1, v18, v19
	v_cvt_pk_bf16_f32 v2, v21, v20
	v_cvt_pk_bf16_f32 v3, v23, v22
	v_cndmask_b32_e32 v14, v14, v16, vcc
	v_cndmask_b32_e32 v16, v17, v30, vcc
	v_cvt_pk_bf16_f32 v6, v16, v14
	v_cvt_pk_bf16_f32 v7, v12, v10
	v_cvt_pk_bf16_f32 v8, v9, v8
	v_cvt_pk_bf16_f32 v9, v13, v11
	global_store_dwordx4 v[58:59], v[0:3], off
	global_store_dwordx4 v[58:59], v[6:9], off offset:512
	s_andn2_b64 exec, exec, s[18:19]
	s_cbranch_execnz .LBB0_292
